# hyena units: redundant back-to-back barriers at the filter-order loop head removed; phase0 cached-K/V bf16 copy loop unrolled (8 loads in flight) for the 256-workgroup grid
# baseline (speedup 1.0000x reference)
.LBB0_97:
	s_or_b64 exec, exec, s[2:3]
	v_lshl_add_u32 v1, s62, 9, v82
	s_mov_b32 s0, 0x80000
	s_lshl_b32 s8, s60, 9
	v_cmp_gt_i32_e32 vcc, s0, v1
	v_lshlrev_b32_e32 v4, 3, v82
	s_and_saveexec_b64 s[0:1], vcc
	s_cbranch_execz .LBB0_100
	s_mov_b32 s6, s58
	v_readlane_b32 s44, v253, 10
	v_readlane_b32 s48, v253, 14
	v_readlane_b32 s49, v253, 15
	v_readlane_b32 s50, v253, 16
	v_readlane_b32 s51, v253, 17
	v_readlane_b32 s58, v253, 24
	v_lshl_add_u32 v5, s62, 12, v4
	s_lshl_b32 s4, s60, 12
	s_mov_b64 s[2:3], 0
	s_mov_b32 s5, 0x3ffff
	v_mov_b32_e32 v6, 0xb400000
	v_mov_b32_e32 v7, 0xb800000
	v_mov_b32_e32 v3, 0
	s_mov_b32 s58, s6
	v_mov_b32_e32 v8, s49
	v_mov_b32_e32 v9, s51
	v_mov_b32_e32 v11, s48
	v_mov_b32_e32 v12, s50
	s_mov_b32 s6, 0x7ffff
	v_mov_b32_e32 v13, v1
	v_readlane_b32 s45, v253, 11
	v_readlane_b32 s46, v253, 12
	v_readlane_b32 s47, v253, 13
	v_readlane_b32 s52, v253, 18
	v_readlane_b32 s53, v253, 19
	v_readlane_b32 s54, v253, 20
	v_readlane_b32 s55, v253, 21
	v_readlane_b32 s56, v253, 22
	v_readlane_b32 s57, v253, 23
	v_readlane_b32 s59, v253, 25
	s_cmp_eq_u32 s60, 0x100
	s_cbranch_scc0 .LBB0_99
	v_lshlrev_b32_e32 v2, 2, v5
	v_add_u32_e32 v14, 0x400000, v2
	v_lshlrev_b32_e32 v22, 1, v5
	v_add_u32_e32 v23, 0x200000, v22
	s_add_u32 s2, s14, 0xb400000
	s_addc_u32 s3, s15, 0
	s_add_u32 s6, s14, 0xb800000
	s_addc_u32 s7, s15, 0
	global_load_dwordx4 v[184:187], v2, s[48:49]
	global_load_dwordx4 v[188:191], v2, s[48:49] offset:16
	global_load_dwordx4 v[192:195], v14, s[48:49]
	global_load_dwordx4 v[204:207], v14, s[48:49] offset:16
	global_load_dwordx4 v[208:211], v2, s[50:51]
	global_load_dwordx4 v[212:215], v2, s[50:51] offset:16
	global_load_dwordx4 v[216:219], v14, s[50:51]
	global_load_dwordx4 v[238:241], v14, s[50:51] offset:16
	s_waitcnt vmcnt(6)
	v_cvt_pk_bf16_f32 v184, v184, v185
	v_cvt_pk_bf16_f32 v185, v186, v187
	v_cvt_pk_bf16_f32 v186, v188, v189
	v_cvt_pk_bf16_f32 v187, v190, v191
	global_store_dwordx4 v22, v[184:187], s[2:3]
	s_waitcnt vmcnt(5)
	v_cvt_pk_bf16_f32 v192, v192, v193
	v_cvt_pk_bf16_f32 v193, v194, v195
	v_cvt_pk_bf16_f32 v194, v204, v205
	v_cvt_pk_bf16_f32 v195, v206, v207
	global_store_dwordx4 v23, v[192:195], s[2:3]
	s_waitcnt vmcnt(4)
	v_cvt_pk_bf16_f32 v208, v208, v209
	v_cvt_pk_bf16_f32 v209, v210, v211
	v_cvt_pk_bf16_f32 v210, v212, v213
	v_cvt_pk_bf16_f32 v211, v214, v215
	global_store_dwordx4 v22, v[208:211], s[6:7]
	s_waitcnt vmcnt(3)
	v_cvt_pk_bf16_f32 v216, v216, v217
	v_cvt_pk_bf16_f32 v217, v218, v219
	v_cvt_pk_bf16_f32 v218, v238, v239
	v_cvt_pk_bf16_f32 v219, v240, v241
	global_store_dwordx4 v23, v[216:219], s[6:7]
	s_branch .LBB0_100

.LBB0_490:
	s_waitcnt lgkmcnt(0)
	s_and_saveexec_b64 s[4:5], s[38:39]
	ds_write_b128 v52, v[6:9]
	s_or_b64 exec, exec, s[4:5]
	s_waitcnt lgkmcnt(0)
	s_barrier
	s_and_saveexec_b64 s[4:5], s[40:41]
	s_cbranch_execz .LBB0_499
	s_add_i32 s16, 0, 0x420
	v_lshlrev_b32_e32 v10, 2, v130
	v_lshl_add_u32 v11, v130, 4, s16
	s_mov_b64 s[16:17], 0
	v_mov_b32_e32 v12, v1
	s_branch .LBB0_495

.LBB0_756:
	s_waitcnt lgkmcnt(0)
	s_and_saveexec_b64 s[2:3], s[38:39]
	ds_write_b128 v45, v[6:9]
	s_or_b64 exec, exec, s[2:3]
	s_waitcnt lgkmcnt(0)
	s_barrier
	s_and_saveexec_b64 s[2:3], s[44:45]
	s_cbranch_execz .LBB0_765
	s_add_i32 s16, 0, 0x2020
	v_lshlrev_b32_e32 v10, 2, v130
	v_lshl_add_u32 v11, v130, 4, s16
	s_mov_b64 s[16:17], 0
	v_mov_b32_e32 v12, v130
	s_branch .LBB0_761
